# memory-attention item: K fragment LDS reads pipelined five deep ahead of the QK MFMAs (on top of the fp8 epilogue rewrite)
# speedup vs baseline: 1.0324x; 1.0016x over previous
; template <int D, int MODE>
; __device__ void attn_item(PP p, int c, int l, int bb, int qb0, int h0) {
;     ...
; #pragma unroll
;       for (int sub = 0; sub < 2; ++sub) {
;         s[sub] = f32x4{0.f, 0.f, 0.f, 0.f};
; #pragma unroll
;         for (int ks = 0; ks < NKS; ++ks) {
;           bf16x8 a = *(const bf16x8*)(Ks + (g * 32 + sub * 16 + fr) * KP + ks * 32 + fq * 8);
;           s[sub] = __builtin_amdgcn_mfma_f32_16x16x32_bf16(a, qf[ks], s[sub], 0, 0, 0);
;         }
;       }
;       float w[8];
;       if (MODE == 1) {
;         float Lv[8], tot = 0.f; bool vld[8];
; #pragma unroll
;         for (int i = 0; i < 8; ++i) {
;           const int rel = r0 + (i >> 2) * 16 + fq * 4 + (i & 3);
;           vld[i] = !masked || (rel < qi);
;           const float z2 = s[i >> 2][i & 3];
;           const float lv = -(fmaxf(z2, 0.f) + flog2(1.0f + fexp2(-fabsf(z2))));
;           Lv[i] = vld[i] ? lv : 0.f;
;           tot += Lv[i];
;         }
;         tot += shx(tot, 16, lane); tot += shx(tot, 32, lane);
;         union { unsigned u[4]; bf16x8 v; } hi, lo;
; #pragma unroll
;         for (int i = 0; i < 4; ++i) {
;           const unsigned hp = cvt_pk_bf16(Lv[2 * i], Lv[2 * i + 1]);
;           hi.u[i] = hp;
;           lo.u[i] = cvt_pk_bf16(Lv[2 * i] - bflo(hp), Lv[2 * i + 1] - bfhi(hp));
;         }
;         f32x4 cs[2];
; #pragma unroll
;         for (int ss_ = 0; ss_ < 2; ++ss_) {
;           cs[ss_] = f32x4{0.f, 0.f, 0.f, 0.f};
;           cs[ss_] = __builtin_amdgcn_mfma_f32_16x16x32_bf16(uop[ss_], hi.v, cs[ss_], 0, 0, 0);
;           cs[ss_] = __builtin_amdgcn_mfma_f32_16x16x32_bf16(uop[ss_], lo.v, cs[ss_], 0, 0, 0);
;         }
; #pragma unroll
;         for (int i = 0; i < 8; ++i) {
;           const float e = s[i >> 2][i & 3] + cs[i >> 2][i & 3] + R;
;           w[i] = vld[i] ? fexp2(e) : 0.f;
;         }
;         R += tot;
;         wdone = __all(R < -150.0f);
;       } else {
;         float gmax = -1e30f;
; #pragma unroll
;         for (int i = 0; i < 8; ++i) {
;           bool v = true;
;           if (MODE == 0) { const int rel = r0 + (i >> 2) * 16 + fq * 4 + (i & 3); v = (rel <= qi) && (rel > qi - 128); }
;           w[i] = v ? s[i >> 2][i & 3] : -1e30f;
;           gmax = fmaxf(gmax, w[i]);
;         }
;         gmax = fmaxf(gmax, shx(gmax, 16, lane)); gmax = fmaxf(gmax, shx(gmax, 32, lane));
;         const float m_new = fmaxf(m_run, gmax);
.LBB0_186:
	v_add_u32_e32 v115, s6, v216
	ds_read_b128 v[134:137], v115
	ds_read_b128 v[178:181], v115 offset:64
	ds_read_b128 v[182:185], v115 offset:128
	ds_read_b128 v[244:247], v115 offset:192
	ds_read_b128 v[248:251], v115 offset:4352
	v_add_u32_e32 v198, 16, v155
	v_mov_b32_e32 v177, v175
	s_addk_i32 s6, 0xde00
	s_cmpk_eq_i32 s6, 0xde00
	s_waitcnt lgkmcnt(4)
	v_mfma_f32_16x16x32_bf16 v[134:137], v[134:137], v[90:93], 0
	s_waitcnt lgkmcnt(3)
	v_mfma_f32_16x16x32_bf16 v[134:137], v[178:181], v[82:85], v[134:137]
	s_waitcnt lgkmcnt(2)
	v_mfma_f32_16x16x32_bf16 v[134:137], v[182:185], v[86:89], v[134:137]
	ds_read_b128 v[182:185], v115 offset:4416
	s_waitcnt lgkmcnt(2)
	v_mfma_f32_16x16x32_bf16 v[134:137], v[244:247], v[94:97], v[134:137]
	ds_read_b128 v[244:247], v115 offset:4480
	s_waitcnt lgkmcnt(2)
	v_mfma_f32_16x16x32_bf16 v[178:181], v[248:251], v[90:93], 0
	ds_read_b128 v[248:251], v115 offset:4544
	s_waitcnt lgkmcnt(2)
	v_mfma_f32_16x16x32_bf16 v[178:181], v[182:185], v[82:85], v[178:181]
	s_waitcnt lgkmcnt(1)
	v_mfma_f32_16x16x32_bf16 v[178:181], v[244:247], v[86:89], v[178:181]
	v_max3_f32 v115, v134, s12, v135
	v_max3_f32 v115, v115, v136, v137
	s_waitcnt lgkmcnt(0)
	v_mfma_f32_16x16x32_bf16 v[178:181], v[248:251], v[94:97], v[178:181]
	s_nop 7
	v_max3_f32 v115, v115, v178, v179
	v_max3_f32 v115, v115, v180, v181
	ds_bpermute_b32 v116, v121, v115
	s_waitcnt lgkmcnt(0)
	v_max_f32_e32 v116, v116, v116
	v_max_f32_e32 v115, v115, v116
	ds_bpermute_b32 v116, v202, v115
	s_waitcnt lgkmcnt(0)
	v_max3_f32 v176, v114, v115, v116
	v_sub_f32_e32 v115, v134, v176
	v_exp_f32_e32 v115, v115
	v_sub_f32_e32 v116, v135, v176
	v_exp_f32_e32 v116, v116
	v_sub_f32_e32 v117, v136, v176
	v_exp_f32_e32 v117, v117
	v_sub_f32_e32 v134, v137, v176
	v_sub_f32_e32 v114, v114, v176
	v_exp_f32_e32 v134, v134
	v_sub_f32_e32 v135, v178, v176
	v_sub_f32_e32 v174, v181, v176
	v_exp_f32_e32 v135, v135
	v_sub_f32_e32 v136, v179, v176
	v_exp_f32_e32 v178, v174
	v_exp_f32_e32 v174, v114
	v_add_f32_e32 v114, 0, v115
	v_exp_f32_e32 v136, v136
	v_sub_f32_e32 v137, v180, v176
	v_add_f32_e32 v114, v116, v114
	v_exp_f32_e32 v137, v137
	v_add_f32_e32 v114, v117, v114
	v_add_f32_e32 v114, v134, v114
	v_add_f32_e32 v114, v135, v114
	v_add_f32_e32 v114, v136, v114
	v_add_f32_e32 v114, v137, v114
	v_pk_mul_f32 v[112:113], v[112:113], v[174:175] op_sel_hi:[1,0]
	v_pk_mul_f32 v[110:111], v[110:111], v[174:175] op_sel_hi:[1,0]
	v_pk_mul_f32 v[108:109], v[108:109], v[174:175] op_sel_hi:[1,0]
	v_pk_mul_f32 v[106:107], v[106:107], v[174:175] op_sel_hi:[1,0]
	v_pk_mul_f32 v[104:105], v[104:105], v[174:175] op_sel_hi:[1,0]
	v_pk_mul_f32 v[102:103], v[102:103], v[174:175] op_sel_hi:[1,0]
	v_pk_mul_f32 v[100:101], v[100:101], v[174:175] op_sel_hi:[1,0]
	v_pk_mul_f32 v[98:99], v[98:99], v[174:175] op_sel_hi:[1,0]
	v_pk_mul_f32 v[80:81], v[80:81], v[174:175] op_sel_hi:[1,0]
	v_pk_mul_f32 v[78:79], v[78:79], v[174:175] op_sel_hi:[1,0]
	v_pk_mul_f32 v[76:77], v[76:77], v[174:175] op_sel_hi:[1,0]
	v_pk_mul_f32 v[74:75], v[74:75], v[174:175] op_sel_hi:[1,0]
	v_pk_mul_f32 v[72:73], v[72:73], v[174:175] op_sel_hi:[1,0]
	v_pk_mul_f32 v[70:71], v[70:71], v[174:175] op_sel_hi:[1,0]
	v_pk_mul_f32 v[68:69], v[68:69], v[174:175] op_sel_hi:[1,0]
	v_pk_mul_f32 v[66:67], v[66:67], v[174:175] op_sel_hi:[1,0]
	v_add_f32_e32 v175, v178, v114
	v_cvt_pk_bf16_f32 v114, v115, v116
	v_cvt_pk_bf16_f32 v115, v117, v134
	v_cvt_pk_bf16_f32 v117, v137, v178
	v_xor_b32_e32 v134, v155, v203
	v_xor_b32_e32 v178, v198, v203
	v_lshl_add_u32 v134, v134, 1, v212
	v_lshl_add_u32 v178, v178, 1, v212
	v_cvt_pk_bf16_f32 v116, v135, v136
	ds_read2st64_b64 v[134:137], v134 offset1:66
	ds_read2st64_b64 v[178:181], v178 offset1:66
	v_fmac_f32_e32 v175, v177, v174
	s_waitcnt lgkmcnt(1)
	v_mov_b32_e32 v182, v134
	v_mov_b32_e32 v183, v135
	s_waitcnt lgkmcnt(0)
	v_mov_b32_e32 v184, v178
	v_mov_b32_e32 v185, v179
	v_xor_b32_e32 v134, v155, v213
	v_lshl_add_u32 v134, v134, 1, v212
	v_add_u32_e32 v134, 0x100, v134
	v_mfma_f32_16x16x32_bf16 v[110:113], v[182:185], v[114:117], v[110:113]
	ds_read2st64_b64 v[182:185], v134 offset0:16 offset1:82
	v_xor_b32_e32 v134, v198, v213
	v_lshl_add_u32 v134, v134, 1, v212
	v_add_u32_e32 v134, 0x100, v134
	ds_read2st64_b64 v[186:189], v134 offset0:16 offset1:82
	s_waitcnt lgkmcnt(1)
	v_mov_b32_e32 v190, v182
	v_mov_b32_e32 v191, v183
	v_xor_b32_e32 v134, v155, v214
	v_lshl_add_u32 v134, v134, 1, v212
	s_waitcnt lgkmcnt(0)
	v_mov_b32_e32 v192, v186
	v_mov_b32_e32 v193, v187
	v_mov_b32_e32 v178, v136
	v_mov_b32_e32 v179, v137
	v_mfma_f32_16x16x32_bf16 v[106:109], v[190:193], v[114:117], v[106:109]
	ds_read2st64_b64 v[190:193], v134 offset0:33 offset1:99
	v_xor_b32_e32 v134, v198, v214
	v_lshl_add_u32 v134, v134, 1, v212
	ds_read2st64_b64 v[194:197], v134 offset0:33 offset1:99
	v_xor_b32_e32 v134, v155, v215
	s_waitcnt lgkmcnt(1)
	v_mov_b32_e32 v220, v190
	v_mov_b32_e32 v221, v191
	v_lshl_add_u32 v134, v134, 1, v212
	s_waitcnt lgkmcnt(0)
	v_mov_b32_e32 v222, v194
	v_mov_b32_e32 v223, v195
	v_add_u32_e32 v134, 0x100, v134
	v_mov_b32_e32 v186, v184
	v_mfma_f32_16x16x32_bf16 v[102:105], v[220:223], v[114:117], v[102:105]
	ds_read2st64_b64 v[220:223], v134 offset0:49 offset1:115
	v_xor_b32_e32 v134, v198, v215
	v_lshl_add_u32 v134, v134, 1, v212
	v_add_u32_e32 v134, 0x100, v134
	ds_read2st64_b64 v[224:227], v134 offset0:49 offset1:115
	s_waitcnt lgkmcnt(1)
	v_mov_b32_e32 v228, v220
	v_mov_b32_e32 v229, v221
	v_mov_b32_e32 v187, v185
	v_mov_b32_e32 v194, v192
	s_waitcnt lgkmcnt(0)
	v_mov_b32_e32 v230, v224
	v_mov_b32_e32 v231, v225
	v_mov_b32_e32 v195, v193
	v_mov_b32_e32 v224, v222
	v_mov_b32_e32 v225, v223
	v_mfma_f32_16x16x32_bf16 v[98:101], v[228:231], v[114:117], v[98:101]
	v_subrev_u32_e32 v155, 32, v155
	v_mfma_f32_16x16x32_bf16 v[78:81], v[178:181], v[114:117], v[78:81]
	v_mfma_f32_16x16x32_bf16 v[74:77], v[186:189], v[114:117], v[74:77]
	v_mfma_f32_16x16x32_bf16 v[70:73], v[194:197], v[114:117], v[70:73]
	v_mfma_f32_16x16x32_bf16 v[66:69], v[224:227], v[114:117], v[66:69]
	v_mov_b32_e32 v114, v176
	s_cbranch_scc0 .LBB0_186
; __device__ __forceinline__ float bflo(unsigned w) { return __uint_as_float(w << 16); }
; __device__ __forceinline__ float bfhi(unsigned w) { return __uint_as_float(w & 0xffff0000u); }
; __device__ __forceinline__ float fexp2(float x) { return __builtin_amdgcn_exp2f(x); }
; __device__ __forceinline__ float siluf_(float x) { return x * sigmoidf_(x); }
; __device__ __forceinline__ float shx(float v, int mask, int lane) { return __int_as_float(__builtin_amdgcn_ds_bpermute((lane ^ mask) << 2, __float_as_int(v))); }
; template <int D, int MODE>
; __device__ void attn_item(PP p, int c, int l, int bb, int qb0, int h0) {
;     ...
;   float inv = 1.0f;
;   if (MODE != 1) {
;     lsum += shx(lsum, 16, lane); lsum += shx(lsum, 32, lane);
;     if (MODE == 0) lsum += fexp2(p->swa_sinks[l * 8 + h] * LOG2E - m_run);
;     inv = 1.0f / lsum;
;   }
; #pragma unroll
;   for (int d = 0; d < NDS; ++d) {
;     const uint2 gv = gvp[d];
;     uint2 pk;
;     pk.x = cvt_pk_bf16(o[d][0] * inv * siluf_(bflo(gv.x)), o[d][1] * inv * siluf_(bfhi(gv.x)));
;     pk.y = cvt_pk_bf16(o[d][2] * inv * siluf_(bflo(gv.y)), o[d][3] * inv * siluf_(bfhi(gv.y)));
;     *(uint2*)(qptr + d * 16 + 4 * fq) = pk;
;   }
	ds_bpermute_b32 v82, v121, v175
	s_mov_b32 s6, 1
	s_mov_b64 s[38:39], 0
	s_waitcnt lgkmcnt(0)
	v_add_f32_e32 v82, v175, v82
	ds_bpermute_b32 v83, v202, v82
	s_waitcnt lgkmcnt(0)
	v_add_f32_e32 v82, v82, v83
	v_div_scale_f32 v83, s[30:31], v82, v82, 1.0
	v_rcp_f32_e32 v84, v83
	s_nop 0
	v_fma_f32 v85, -v83, v84, 1.0
	v_fmac_f32_e32 v84, v85, v84
	v_div_scale_f32 v85, vcc, 1.0, v82, 1.0
	v_mul_f32_e32 v86, v85, v84
	v_fma_f32 v87, -v83, v86, v85
	v_fmac_f32_e32 v86, v87, v84
	v_fma_f32 v83, -v83, v86, v85
	v_div_fmas_f32 v83, v83, v84, v86
	s_waitcnt vmcnt(3)
	v_lshlrev_b32_e32 v86, 16, v170
	v_lshl_add_u64 v[84:85], v[172:173], 0, v[0:1]
	v_mul_f32_e32 v0, 0xbfb8aa3b, v86
	v_exp_f32_e32 v0, v0
	v_and_b32_e32 v87, 0xffff0000, v170
	v_div_fixup_f32 v82, v83, v82, 1.0
	v_pk_mul_f32 v[90:91], v[110:111], v[82:83] op_sel_hi:[1,0]
	v_add_f32_e32 v0, 1.0, v0
	v_rcp_f32_e32 v88, v0
	v_mul_f32_e32 v0, 0xbfb8aa3b, v87
	v_exp_f32_e32 v0, v0
	v_pk_mul_f32 v[92:93], v[112:113], v[82:83] op_sel_hi:[1,0]
	v_pk_mul_f32 v[78:79], v[78:79], v[82:83] op_sel_hi:[1,0]
	v_pk_mul_f32 v[80:81], v[80:81], v[82:83] op_sel_hi:[1,0]
	v_add_f32_e32 v0, 1.0, v0
	v_rcp_f32_e32 v89, v0
	v_pk_mul_f32 v[74:75], v[74:75], v[82:83] op_sel_hi:[1,0]
	v_pk_mul_f32 v[76:77], v[76:77], v[82:83] op_sel_hi:[1,0]
	v_pk_mul_f32 v[70:71], v[70:71], v[82:83] op_sel_hi:[1,0]
	v_pk_mul_f32 v[86:87], v[88:89], v[86:87]
	v_lshlrev_b32_e32 v88, 16, v171
	v_mul_f32_e32 v0, 0xbfb8aa3b, v88
	v_exp_f32_e32 v0, v0
	v_and_b32_e32 v89, 0xffff0000, v171
	v_pk_mul_f32 v[86:87], v[86:87], v[90:91]
	v_pk_mul_f32 v[72:73], v[72:73], v[82:83] op_sel_hi:[1,0]
	v_add_f32_e32 v0, 1.0, v0
	v_rcp_f32_e32 v90, v0
	v_mul_f32_e32 v0, 0xbfb8aa3b, v89
	v_exp_f32_e32 v0, v0
	v_cvt_pk_bf16_f32 v86, v86, v87
	v_pk_mul_f32 v[66:67], v[66:67], v[82:83] op_sel_hi:[1,0]
	v_pk_mul_f32 v[68:69], v[68:69], v[82:83] op_sel_hi:[1,0]
	v_add_f32_e32 v0, 1.0, v0
	v_rcp_f32_e32 v91, v0
	s_and_b64 vcc, exec, s[42:43]
	v_pk_mul_f32 v[88:89], v[90:91], v[88:89]
	s_nop 0
	v_pk_mul_f32 v[88:89], v[88:89], v[92:93]
	v_pk_mul_f32 v[90:91], v[106:107], v[82:83] op_sel_hi:[1,0]
	v_cvt_pk_bf16_f32 v87, v88, v89
	global_store_dwordx2 v[84:85], v[86:87], off
	v_lshlrev_b32_e32 v86, 16, v168
	v_mul_f32_e32 v0, 0xbfb8aa3b, v86
	v_exp_f32_e32 v0, v0
	v_and_b32_e32 v87, 0xffff0000, v168
	v_pk_mul_f32 v[92:93], v[108:109], v[82:83] op_sel_hi:[1,0]
	v_add_f32_e32 v0, 1.0, v0
	v_rcp_f32_e32 v88, v0
	v_mul_f32_e32 v0, 0xbfb8aa3b, v87
	v_exp_f32_e32 v0, v0
	s_nop 0
	v_add_f32_e32 v0, 1.0, v0
	v_rcp_f32_e32 v89, v0
	s_nop 0
	v_pk_mul_f32 v[86:87], v[88:89], v[86:87]
	v_lshlrev_b32_e32 v88, 16, v169
	v_mul_f32_e32 v0, 0xbfb8aa3b, v88
	v_exp_f32_e32 v0, v0
	v_and_b32_e32 v89, 0xffff0000, v169
	v_pk_mul_f32 v[86:87], v[86:87], v[90:91]
	v_add_f32_e32 v0, 1.0, v0
	v_rcp_f32_e32 v90, v0
	v_mul_f32_e32 v0, 0xbfb8aa3b, v89
	v_exp_f32_e32 v0, v0
	v_cvt_pk_bf16_f32 v86, v86, v87
	v_add_f32_e32 v0, 1.0, v0
	v_rcp_f32_e32 v91, v0
	s_nop 0
	v_pk_mul_f32 v[88:89], v[90:91], v[88:89]
	s_nop 0
	v_pk_mul_f32 v[88:89], v[88:89], v[92:93]
	v_pk_mul_f32 v[90:91], v[102:103], v[82:83] op_sel_hi:[1,0]
	v_cvt_pk_bf16_f32 v87, v88, v89
	global_store_dwordx2 v[84:85], v[86:87], off offset:32
	v_lshlrev_b32_e32 v86, 16, v166
	v_mul_f32_e32 v0, 0xbfb8aa3b, v86
	v_exp_f32_e32 v0, v0
	v_and_b32_e32 v87, 0xffff0000, v166
	v_pk_mul_f32 v[92:93], v[104:105], v[82:83] op_sel_hi:[1,0]
	v_add_f32_e32 v0, 1.0, v0
	v_rcp_f32_e32 v88, v0
	v_mul_f32_e32 v0, 0xbfb8aa3b, v87
	v_exp_f32_e32 v0, v0
	s_nop 0
	v_add_f32_e32 v0, 1.0, v0
	v_rcp_f32_e32 v89, v0
	s_nop 0
	v_pk_mul_f32 v[86:87], v[88:89], v[86:87]
	v_lshlrev_b32_e32 v88, 16, v167
	v_mul_f32_e32 v0, 0xbfb8aa3b, v88
	v_exp_f32_e32 v0, v0
	v_and_b32_e32 v89, 0xffff0000, v167
	v_pk_mul_f32 v[86:87], v[86:87], v[90:91]
	v_add_f32_e32 v0, 1.0, v0
	v_rcp_f32_e32 v90, v0
	v_mul_f32_e32 v0, 0xbfb8aa3b, v89
	v_exp_f32_e32 v0, v0
	v_cvt_pk_bf16_f32 v86, v86, v87
	v_add_f32_e32 v0, 1.0, v0
	v_rcp_f32_e32 v91, v0
	s_nop 0
	v_pk_mul_f32 v[88:89], v[90:91], v[88:89]
	s_nop 0
	v_pk_mul_f32 v[88:89], v[88:89], v[92:93]
	v_pk_mul_f32 v[90:91], v[98:99], v[82:83] op_sel_hi:[1,0]
	v_cvt_pk_bf16_f32 v87, v88, v89
	global_store_dwordx2 v[84:85], v[86:87], off offset:64
	v_lshlrev_b32_e32 v86, 16, v164
	v_mul_f32_e32 v0, 0xbfb8aa3b, v86
	v_exp_f32_e32 v0, v0
	v_and_b32_e32 v87, 0xffff0000, v164
	v_pk_mul_f32 v[92:93], v[100:101], v[82:83] op_sel_hi:[1,0]
	v_add_f32_e32 v0, 1.0, v0
	v_rcp_f32_e32 v88, v0
	v_mul_f32_e32 v0, 0xbfb8aa3b, v87
	v_exp_f32_e32 v0, v0
	s_nop 0
	v_add_f32_e32 v0, 1.0, v0
	v_rcp_f32_e32 v89, v0
	s_nop 0
	v_pk_mul_f32 v[86:87], v[88:89], v[86:87]
	v_lshlrev_b32_e32 v88, 16, v165
	v_mul_f32_e32 v0, 0xbfb8aa3b, v88
	v_exp_f32_e32 v0, v0
	v_and_b32_e32 v89, 0xffff0000, v165
	v_pk_mul_f32 v[86:87], v[86:87], v[90:91]
	v_add_f32_e32 v0, 1.0, v0
	v_rcp_f32_e32 v90, v0
	v_mul_f32_e32 v0, 0xbfb8aa3b, v89
	v_exp_f32_e32 v0, v0
	v_cvt_pk_bf16_f32 v86, v86, v87
	v_add_f32_e32 v0, 1.0, v0
	v_rcp_f32_e32 v91, v0
	s_nop 0
	v_pk_mul_f32 v[88:89], v[90:91], v[88:89]
	s_nop 0
	v_pk_mul_f32 v[88:89], v[88:89], v[92:93]
	s_nop 0
	v_cvt_pk_bf16_f32 v87, v88, v89
	global_store_dwordx2 v[84:85], v[86:87], off offset:96
	v_lshlrev_b32_e32 v86, 16, v162
	v_mul_f32_e32 v0, 0xbfb8aa3b, v86
	v_exp_f32_e32 v0, v0
	v_and_b32_e32 v87, 0xffff0000, v162
	v_add_f32_e32 v0, 1.0, v0
	v_rcp_f32_e32 v88, v0
	v_mul_f32_e32 v0, 0xbfb8aa3b, v87
	v_exp_f32_e32 v0, v0
	s_nop 0
	v_add_f32_e32 v0, 1.0, v0
	v_rcp_f32_e32 v89, v0
	s_nop 0
	v_pk_mul_f32 v[86:87], v[88:89], v[86:87]
	s_nop 0
	v_pk_mul_f32 v[78:79], v[86:87], v[78:79]
	v_lshlrev_b32_e32 v86, 16, v163
	v_mul_f32_e32 v0, 0xbfb8aa3b, v86
	v_exp_f32_e32 v0, v0
	v_and_b32_e32 v87, 0xffff0000, v163
	v_cvt_pk_bf16_f32 v78, v78, v79
	v_add_f32_e32 v0, 1.0, v0
	v_rcp_f32_e32 v88, v0
	v_mul_f32_e32 v0, 0xbfb8aa3b, v87
	v_exp_f32_e32 v0, v0
	s_nop 0
	v_add_f32_e32 v0, 1.0, v0
	v_rcp_f32_e32 v89, v0
	s_nop 0
	v_pk_mul_f32 v[86:87], v[88:89], v[86:87]
	s_nop 0
	v_pk_mul_f32 v[80:81], v[86:87], v[80:81]
	s_nop 0
	v_cvt_pk_bf16_f32 v79, v80, v81
	global_store_dwordx2 v[84:85], v[78:79], off offset:128
	s_waitcnt vmcnt(7)
; __device__ __forceinline__ float bflo(unsigned w) { return __uint_as_float(w << 16); }
; __device__ __forceinline__ float bfhi(unsigned w) { return __uint_as_float(w & 0xffff0000u); }
; __device__ __forceinline__ float siluf_(float x) { return x * sigmoidf_(x); }
; template <int D, int MODE>
; __device__ void attn_item(PP p, int c, int l, int bb, int qb0, int h0) {
;     ...
; #pragma unroll
;   for (int d = 0; d < NDS; ++d) {
;     const uint2 gv = gvp[d];
;     uint2 pk;
;     pk.x = cvt_pk_bf16(o[d][0] * inv * siluf_(bflo(gv.x)), o[d][1] * inv * siluf_(bfhi(gv.x)));
;     pk.y = cvt_pk_bf16(o[d][2] * inv * siluf_(bflo(gv.y)), o[d][3] * inv * siluf_(bfhi(gv.y)));
;     *(uint2*)(qptr + d * 16 + 4 * fq) = pk;
;   }
	v_lshlrev_b32_e32 v78, 16, v160
	v_mul_f32_e32 v0, 0xbfb8aa3b, v78
	v_exp_f32_e32 v0, v0
	v_and_b32_e32 v79, 0xffff0000, v160
	v_add_f32_e32 v0, 1.0, v0
	v_rcp_f32_e32 v80, v0
	v_mul_f32_e32 v0, 0xbfb8aa3b, v79
	v_exp_f32_e32 v0, v0
	s_nop 0
	v_add_f32_e32 v0, 1.0, v0
	v_rcp_f32_e32 v81, v0
	s_nop 0
	v_pk_mul_f32 v[78:79], v[80:81], v[78:79]
	s_nop 0
	v_pk_mul_f32 v[74:75], v[78:79], v[74:75]
	v_lshlrev_b32_e32 v78, 16, v161
	v_mul_f32_e32 v0, 0xbfb8aa3b, v78
	v_exp_f32_e32 v0, v0
	v_and_b32_e32 v79, 0xffff0000, v161
	v_cvt_pk_bf16_f32 v74, v74, v75
	v_add_f32_e32 v0, 1.0, v0
	v_rcp_f32_e32 v80, v0
	v_mul_f32_e32 v0, 0xbfb8aa3b, v79
	v_exp_f32_e32 v0, v0
	s_nop 0
	v_add_f32_e32 v0, 1.0, v0
	v_rcp_f32_e32 v81, v0
	s_nop 0
	v_pk_mul_f32 v[78:79], v[80:81], v[78:79]
	s_nop 0
	v_pk_mul_f32 v[76:77], v[78:79], v[76:77]
	s_nop 0
	v_cvt_pk_bf16_f32 v75, v76, v77
	global_store_dwordx2 v[84:85], v[74:75], off offset:160
	s_waitcnt vmcnt(7)
	v_lshlrev_b32_e32 v74, 16, v158
	v_mul_f32_e32 v0, 0xbfb8aa3b, v74
	v_exp_f32_e32 v0, v0
	v_and_b32_e32 v75, 0xffff0000, v158
	v_add_f32_e32 v0, 1.0, v0
	v_rcp_f32_e32 v76, v0
	v_mul_f32_e32 v0, 0xbfb8aa3b, v75
	v_exp_f32_e32 v0, v0
	s_nop 0
	v_add_f32_e32 v0, 1.0, v0
	v_rcp_f32_e32 v77, v0
	s_nop 0
	v_pk_mul_f32 v[74:75], v[76:77], v[74:75]
	s_nop 0
	v_pk_mul_f32 v[70:71], v[74:75], v[70:71]
	v_lshlrev_b32_e32 v74, 16, v159
	v_mul_f32_e32 v0, 0xbfb8aa3b, v74
	v_exp_f32_e32 v0, v0
	v_and_b32_e32 v75, 0xffff0000, v159
	v_cvt_pk_bf16_f32 v70, v70, v71
	v_add_f32_e32 v0, 1.0, v0
	v_rcp_f32_e32 v76, v0
	v_mul_f32_e32 v0, 0xbfb8aa3b, v75
	v_exp_f32_e32 v0, v0
	s_nop 0
	v_add_f32_e32 v0, 1.0, v0
	v_rcp_f32_e32 v77, v0
	s_nop 0
	v_pk_mul_f32 v[74:75], v[76:77], v[74:75]
	s_nop 0
	v_pk_mul_f32 v[72:73], v[74:75], v[72:73]
	s_nop 0
	v_cvt_pk_bf16_f32 v71, v72, v73
	global_store_dwordx2 v[84:85], v[70:71], off offset:192
	s_waitcnt vmcnt(7)
	v_lshlrev_b32_e32 v70, 16, v156
	v_mul_f32_e32 v0, 0xbfb8aa3b, v70
	v_exp_f32_e32 v0, v0
	v_and_b32_e32 v71, 0xffff0000, v156
	v_add_f32_e32 v0, 1.0, v0
	v_rcp_f32_e32 v72, v0
	v_mul_f32_e32 v0, 0xbfb8aa3b, v71
	v_exp_f32_e32 v0, v0
	s_nop 0
	v_add_f32_e32 v0, 1.0, v0
	v_rcp_f32_e32 v73, v0
	s_nop 0
	v_pk_mul_f32 v[70:71], v[72:73], v[70:71]
	s_nop 0
	v_pk_mul_f32 v[66:67], v[70:71], v[66:67]
	v_lshlrev_b32_e32 v70, 16, v157
	v_mul_f32_e32 v0, 0xbfb8aa3b, v70
	v_exp_f32_e32 v0, v0
	v_and_b32_e32 v71, 0xffff0000, v157
	v_cvt_pk_bf16_f32 v66, v66, v67
	v_add_f32_e32 v0, 1.0, v0
	v_rcp_f32_e32 v72, v0
	v_mul_f32_e32 v0, 0xbfb8aa3b, v71
	v_exp_f32_e32 v0, v0
	s_nop 0
	v_add_f32_e32 v0, 1.0, v0
	v_rcp_f32_e32 v73, v0
	s_nop 0
	v_pk_mul_f32 v[70:71], v[72:73], v[70:71]
	s_nop 0
	v_pk_mul_f32 v[68:69], v[70:71], v[68:69]
	s_nop 0
	v_cvt_pk_bf16_f32 v67, v68, v69
	global_store_dwordx2 v[84:85], v[66:67], off offset:224
	s_cbranch_vccz .LBB0_181
